# PH1: nt (non-temporal) hint on the once-read streaming row loads; modulation-vector loads keep the default policy
# speedup vs baseline: 1.0018x; 1.0018x over previous
;     ...
;     if (gw < nrows) { const float* s0_ = (gw < ML) ? srcL + (size_t)gw * D : srcC + (size_t)(gw - ML) * D;
; #pragma unroll
;         for (int j = 0; j < 8; ++j) nv[j] = *(const f32x4*)(s0_ + lane * 4 + 256 * j); }
;     for (int m = gw; m < nrows; m += NGW) {
;         float* dst; int mv;
;         if (m < ML) { dst = dstL + (size_t)m * D; mv = (m >= SEQ) ? 1 : 0; }
;         else { dst = dstC + (size_t)(m - ML) * D; mv = 2; }
;         f32x4 v[8];
; #pragma unroll
;         for (int j = 0; j < 8; ++j) v[j] = nv[j];
;         { const int mn = m + NGW;
;           if (mn < nrows) { const float* s1_ = (mn < ML) ? srcL + (size_t)mn * D : srcC + (size_t)(mn - ML) * D;
; #pragma unroll
;               for (int j = 0; j < 8; ++j) nv[j] = *(const f32x4*)(s1_ + lane * 4 + 256 * j); } }
;     ...
;             if (l == 0 && PHON(0)) rowwise(gw, NGW, lane, MT, in.p[0], in.p[2], XL, XC, false, in.p[22], in.p[23], true, modl, 0, 1, AC);
.LBB0_53:
	s_cmp_lt_i32 s72, 2
	s_cselect_b64 s[4:5], -1, 0
	s_cmp_gt_i32 s73, 1
	v_writelane_b32 v246, s68, 31
	s_cselect_b64 s[6:7], -1, 0
	s_and_b64 s[4:5], s[4:5], s[6:7]
	v_writelane_b32 v246, s69, 32
	v_writelane_b32 v246, s70, 33
	v_writelane_b32 v246, s71, 34
	v_writelane_b32 v246, s72, 35
	v_writelane_b32 v246, s73, 36
	s_andn2_b64 vcc, exec, s[4:5]
	v_writelane_b32 v246, s74, 37
	v_writelane_b32 v246, s75, 38
	s_cbranch_vccnz .LBB0_113
	v_readfirstlane_b32 s3, v174
	v_readlane_b32 s2, v246, 0
	s_lshr_b32 s3, s3, 6
	s_lshl_b32 s4, s2, 3
	s_waitcnt lgkmcnt(0)
	s_add_i32 s12, s3, s4
	s_cmpk_gt_i32 s12, 0x41ff
	s_cbranch_scc1 .LBB0_59
	v_readlane_b32 s16, v246, 15
	v_readlane_b32 s17, v246, 16
	v_readlane_b32 s20, v246, 19
	v_readlane_b32 s21, v246, 20
	s_lshl_b32 s4, s74, 3
	s_lshl_b32 s5, s74, 3
	v_and_b32_e32 v168, 63, v174
	v_lshlrev_b32_e32 v170, 3, v168
	v_lshlrev_b32_e32 v168, 4, v168
	s_mov_b32 s13, -1
	s_add_u32 s24, s70, 0x6700000
	s_addc_u32 s25, s71, 0
	s_add_i32 s8, s12, 0xffffc000
	s_cmpk_lt_i32 s12, 0x4000
	s_cselect_b32 s6, s16, s20
	s_cselect_b32 s7, s17, s21
	s_cselect_b32 s8, s12, s8
	s_lshl_b32 s8, s8, 13
	s_add_u32 s6, s6, s8
	s_addc_u32 s7, s7, 0
	s_add_u32 s10, s6, 0x1000
	s_addc_u32 s11, s7, 0
	global_load_dwordx4 v[0:3], v168, s[6:7] nt
	global_load_dwordx4 v[4:7], v168, s[6:7] offset:1024 nt
	global_load_dwordx4 v[8:11], v168, s[6:7] offset:2048 nt
	global_load_dwordx4 v[12:15], v168, s[6:7] offset:3072 nt
	global_load_dwordx4 v[16:19], v168, s[10:11] nt
	global_load_dwordx4 v[20:23], v168, s[10:11] offset:1024 nt
	global_load_dwordx4 v[24:27], v168, s[10:11] offset:2048 nt
	global_load_dwordx4 v[28:31], v168, s[10:11] offset:3072 nt
.Lp1_it0:
	s_waitcnt vmcnt(8)
	s_add_i32 s14, s12, s5
	s_cmpk_lt_i32 s14, 0x4200
	s_cbranch_scc0 .Lp1_nopf0
	s_add_i32 s8, s14, 0xffffc000
	s_cmpk_lt_i32 s14, 0x4000
	s_cselect_b32 s6, s16, s20
	s_cselect_b32 s7, s17, s21
	s_cselect_b32 s8, s14, s8
	s_lshl_b32 s8, s8, 13
	s_add_u32 s6, s6, s8
	s_addc_u32 s7, s7, 0
	s_add_u32 s10, s6, 0x1000
	s_addc_u32 s11, s7, 0
	global_load_dwordx4 v[32:35], v168, s[6:7] nt
	global_load_dwordx4 v[36:39], v168, s[6:7] offset:1024 nt
	global_load_dwordx4 v[40:43], v168, s[6:7] offset:2048 nt
	global_load_dwordx4 v[44:47], v168, s[6:7] offset:3072 nt
	global_load_dwordx4 v[48:51], v168, s[10:11] nt
	global_load_dwordx4 v[52:55], v168, s[10:11] offset:1024 nt
	global_load_dwordx4 v[56:59], v168, s[10:11] offset:2048 nt
	global_load_dwordx4 v[60:63], v168, s[10:11] offset:3072 nt

;     ...
;     for (int m = gw; m < nrows; m += NGW) {
;         float* dst; int mv;
;         if (m < ML) { dst = dstL + (size_t)m * D; mv = (m >= SEQ) ? 1 : 0; }
;         else { dst = dstC + (size_t)(m - ML) * D; mv = 2; }
;         f32x4 v[8];
; #pragma unroll
;         for (int j = 0; j < 8; ++j) v[j] = nv[j];
;         { const int mn = m + NGW;
;           if (mn < nrows) { const float* s1_ = (mn < ML) ? srcL + (size_t)mn * D : srcC + (size_t)(mn - ML) * D;
; #pragma unroll
;               for (int j = 0; j < 8; ++j) nv[j] = *(const f32x4*)(s1_ + lane * 4 + 256 * j); } }
.Lp1_it1:
	s_waitcnt vmcnt(8)
	s_add_i32 s14, s12, s5
	s_cmpk_lt_i32 s14, 0x4200
	s_cbranch_scc0 .Lp1_nopf1
	s_add_i32 s8, s14, 0xffffc000
	s_cmpk_lt_i32 s14, 0x4000
	s_cselect_b32 s6, s16, s20
	s_cselect_b32 s7, s17, s21
	s_cselect_b32 s8, s14, s8
	s_lshl_b32 s8, s8, 13
	s_add_u32 s6, s6, s8
	s_addc_u32 s7, s7, 0
	s_add_u32 s10, s6, 0x1000
	s_addc_u32 s11, s7, 0
	global_load_dwordx4 v[0:3], v168, s[6:7] nt
	global_load_dwordx4 v[4:7], v168, s[6:7] offset:1024 nt
	global_load_dwordx4 v[8:11], v168, s[6:7] offset:2048 nt
	global_load_dwordx4 v[12:15], v168, s[6:7] offset:3072 nt
	global_load_dwordx4 v[16:19], v168, s[10:11] nt
	global_load_dwordx4 v[20:23], v168, s[10:11] offset:1024 nt
	global_load_dwordx4 v[24:27], v168, s[10:11] offset:2048 nt
	global_load_dwordx4 v[28:31], v168, s[10:11] offset:3072 nt
